# scan Q/K/V LDS-DMA tile loads marked nt (read-once streaming data); otherwise as previous version
# speedup vs baseline: 1.0103x; 1.0018x over previous
.LBB0_492:
	s_cmp_gt_u32 s41, 1
	s_cselect_b32 s2, 35, 1
	s_sub_i32 s8, s2, s41
	s_and_b64 s[2:3], s[4:5], exec
	s_cselect_b32 s2, s41, s8
	s_lshl_b32 s2, s2, 7
	s_ashr_i32 s3, s2, 31
	v_and_b32_e32 v155, 63, v140
	s_add_u32 s16, s38, s2
	s_addc_u32 s17, s39, s3
	v_lshlrev_b32_e32 v66, 4, v155
	s_lshl_b64 s[2:3], s[16:17], s96
	v_or_b32_e32 v67, s65, v66
	v_or_b32_e32 v70, s70, v66
	s_lshl_b64 s[2:3], s[2:3], 1
	v_and_b32_e32 v156, 15, v140
	v_lshrrev_b32_e32 v68, 8, v67
	v_lshrrev_b32_e32 v67, 6, v67
	v_lshrrev_b32_e32 v71, 8, v70
	v_lshrrev_b32_e32 v70, 6, v70
	v_or_b32_e32 v73, s71, v66
	s_add_u32 s8, s0, s2
	v_bitop3_b32 v67, v67, v156, 12 bitop3:0x6c
	v_and_b32_e32 v70, 12, v70
	v_lshrrev_b32_e32 v74, 8, v73
	v_lshrrev_b32_e32 v73, 6, v73
	s_addc_u32 s9, s55, s3
	v_lshlrev_b32_e32 v67, 4, v67
	s_add_i32 s10, s65, 0
	v_bitop3_b32 v70, v70, v156, 1 bitop3:0x36
	v_and_b32_e32 v73, 12, v73
	v_or_b32_e32 v66, s76, v66
	v_lshl_or_b32 v69, v68, s77, v67
	s_mov_b32 m0, s10
	v_lshlrev_b32_e32 v70, 4, v70
	v_bitop3_b32 v73, v73, v156, 2 bitop3:0x36
	v_lshrrev_b32_e32 v76, 8, v66
	v_lshrrev_b32_e32 v66, 6, v66
	global_load_lds_dwordx4 v69, s[8:9] nt
	v_lshl_or_b32 v72, v71, s77, v70
	s_add_i32 m0, s10, 0x400
	v_lshlrev_b32_e32 v73, 4, v73
	v_and_b32_e32 v66, 12, v66
	global_load_lds_dwordx4 v72, s[8:9] nt
	v_lshl_or_b32 v75, v74, s77, v73
	s_add_i32 m0, s10, 0x800
	v_bitop3_b32 v66, v66, v156, 3 bitop3:0x36
	global_load_lds_dwordx4 v75, s[8:9] nt
	v_lshlrev_b32_e32 v77, 4, v66
	s_add_i32 m0, s10, 0xc00
	v_lshl_or_b32 v66, v76, s77, v77
	s_add_u32 s2, s80, s2
	global_load_lds_dwordx4 v66, s[8:9] nt
	s_addc_u32 s3, s66, s3
	s_add_i32 m0, s10, 0x8000
	v_lshl_or_b32 v190, v68, 14, v67
	global_load_lds_dwordx4 v69, s[2:3] nt
	s_add_i32 m0, s10, 0x8400
	s_nop 0
	global_load_lds_dwordx4 v72, s[2:3] nt
	s_add_i32 m0, s10, 0x8800
	s_nop 0
	global_load_lds_dwordx4 v75, s[2:3] nt
	s_add_i32 m0, s10, 0x8c00
	s_nop 0
	global_load_lds_dwordx4 v66, s[2:3] nt
	s_lshl_b64 s[2:3], s[16:17], 14
	s_add_u32 s2, s67, s2
	s_addc_u32 s3, s18, s3
	s_add_i32 s8, 0, 0x10000
	s_add_i32 m0, s8, s65
	v_lshl_add_u64 v[66:67], s[2:3], 0, v[190:191]
	global_load_lds_dwordx4 v190, s[2:3] nt
	v_lshl_or_b32 v190, v71, 14, v70
	s_add_i32 m0, s8, s70
	v_lshl_add_u64 v[68:69], s[2:3], 0, v[190:191]
	global_load_lds_dwordx4 v190, s[2:3] nt
	v_lshl_or_b32 v190, v74, 14, v73
	s_add_i32 m0, s8, s71
	v_lshl_add_u64 v[70:71], s[2:3], 0, v[190:191]
	global_load_lds_dwordx4 v190, s[2:3] nt
	v_lshl_or_b32 v190, v76, 14, v77
	s_add_i32 m0, s8, s76
	v_lshl_add_u64 v[72:73], s[2:3], 0, v[190:191]
	global_load_lds_dwordx4 v190, s[2:3] nt
	s_add_i32 s2, 0, 0x18000
	v_lshl_add_u64 v[66:67], v[66:67], 0, s[50:51]
	s_add_i32 m0, s2, s65
	s_nop 0
	global_load_lds_dwordx4 v[66:67], off nt
	v_lshl_add_u64 v[66:67], v[68:69], 0, s[50:51]
	s_add_i32 m0, s2, s70
	s_nop 0
	global_load_lds_dwordx4 v[66:67], off nt
	v_lshl_add_u64 v[66:67], v[70:71], 0, s[50:51]
	s_add_i32 m0, s2, s71
	s_nop 0
	global_load_lds_dwordx4 v[66:67], off nt
	v_lshl_add_u64 v[66:67], v[72:73], 0, s[50:51]
	s_add_i32 m0, s2, s76
	s_cmp_eq_u32 s41, 33
	global_load_lds_dwordx4 v[66:67], off nt
	s_waitcnt vmcnt(8)
	s_waitcnt lgkmcnt(0)
	s_barrier
	s_cselect_b64 s[2:3], -1, 0
	s_xor_b64 s[8:9], s[90:91], -1
	s_or_b64 s[2:3], s[8:9], s[2:3]
	s_and_b64 vcc, exec, s[2:3]
	s_cbranch_vccnz .LBB0_496
	s_add_i32 s8, s41, 1
	s_sub_i32 s2, 34, s41
	s_cmp_lg_u32 s41, 0
	s_cselect_b32 s9, s2, 0
	s_and_b64 s[2:3], s[4:5], exec
	s_cselect_b32 s2, s8, s9
	s_lshl_b32 s2, s2, 7
	s_add_u32 s2, s19, s2
	s_addc_u32 s3, s33, 0
	s_add_u32 s8, s2, s46
	s_addc_u32 s9, s3, 0
	s_lshl_b64 s[8:9], s[8:9], 3
	s_add_u32 s8, s8, s60
	s_addc_u32 s9, s9, s61
	s_lshl_b64 s[8:9], s[8:9], 2
	s_add_u32 s10, s82, s8
	s_addc_u32 s11, s83, s9
	s_add_u32 s8, s84, s8
	s_addc_u32 s9, s85, s9
	global_load_dword v139, v191, s[10:11]
	global_load_dword v151, v191, s[8:9]
	v_cmp_gt_i32_e32 vcc, s74, v140
	s_and_saveexec_b64 s[8:9], vcc
	s_cbranch_execz .LBB0_495
	v_ashrrev_i32_e32 v141, 31, v140
	v_lshl_add_u64 v[66:67], s[2:3], 0, v[140:141]
	v_lshl_add_u64 v[66:67], v[66:67], 3, s[60:61]
	v_readlane_b32 s2, v254, 48
	v_lshlrev_b64 v[66:67], 2, v[66:67]
	v_readlane_b32 s3, v254, 49
	s_nop 1
	v_lshl_add_u64 v[68:69], s[2:3], 0, v[66:67]
	global_load_dword v150, v[68:69], off
	v_lshl_add_u64 v[68:69], s[82:83], 0, v[66:67]
	v_lshl_add_u64 v[66:67], s[84:85], 0, v[66:67]
	global_load_dword v152, v[68:69], off
	global_load_dword v153, v[66:67], off
